# v91 + one static s_setprio 1 at kernel entry for waves 4-7 (younger half), kept for the whole kernel
# baseline (speedup 1.0000x reference)
; #define LAS __attribute__((address_space(3)))
; __global__ void __launch_bounds__(NW * 64, 2) fwd_kernel(Args a) {
;     extern __shared__ __attribute__((aligned(16))) unsigned char lds_raw[];
;     LAS unsigned char* lds = (LAS unsigned char*)lds_raw;
;     unsigned char* ws = a.ws;
;     stat_t* RS = (stat_t*)(ws + WS_RS); stat_t* RSV = RS + 9 * M;
;     bf16* XB = (bf16*)(ws + WS_XB); bf16* ACT = (bf16*)(ws + WS_ACT); unsigned char* R = ws + WS_R;
;     const int G = gridDim.x;
;     if (threadIdx.x < 4) ((LAS unsigned*)(lds + BARST_OFF))[threadIdx.x] = 0u;
;     if (a.ph_lo == 0 && blockIdx.x == 0) { unsigned* bw = (unsigned*)(ws + WS_BAR); for (int i = threadIdx.x; i < XCD_BAR_WORDS; i += NW * 64) bw[i] = 0u; }
;     __syncthreads();
;     XcdBarrier bar; bar.bar = (unsigned*)(ws + WS_BAR); bar.x = 0; bar.st = (volatile LAS unsigned*)(lds + BARST_OFF);
_Z10fwd_kernel4Args:
	s_load_dwordx8 s[4:11], s[0:1], 0x80
	s_load_dwordx2 s[34:35], s[0:1], 0xa0
	s_load_dwordx4 s[20:23], s[0:1], 0xa8
	v_writelane_b32 v252, s2, 0
	s_add_u32 s2, s0, 0xb8
	s_addc_u32 s3, s1, 0
	s_waitcnt lgkmcnt(0)
	v_writelane_b32 v252, s4, 1
	v_and_b32_e32 v246, 0x3ff, v0
	v_readfirstlane_b32 s98, v246
	s_nop 0
	s_bitcmp1_b32 s98, 8
	s_cbranch_scc0 .Lprio_all
	s_setprio 1
.Lprio_all:
	v_cmp_gt_u32_e32 vcc, 4, v246
	v_writelane_b32 v252, s5, 2
	v_writelane_b32 v252, s6, 3
	v_writelane_b32 v252, s7, 4
	v_writelane_b32 v252, s8, 5
	v_writelane_b32 v252, s9, 6
	v_writelane_b32 v252, s10, 7
	v_writelane_b32 v252, s11, 8
	v_writelane_b32 v252, s2, 9
	s_nop 1
	v_writelane_b32 v252, s3, 10
	s_and_saveexec_b64 s[4:5], vcc
	v_lshl_add_u32 v1, v246, 2, 0
	v_add_u32_e32 v1, 0x22000, v1
	v_mov_b32_e32 v2, 0
	ds_write_b32 v1, v2
	s_or_b64 exec, exec, s[4:5]
	s_load_dword s16, s[0:1], 0xb8
	v_readlane_b32 s2, v252, 0
	s_or_b32 s2, s20, s2
	s_cmp_lg_u32 s2, 0
	s_mov_b32 s6, 0
	s_cbranch_scc1 .LBB0_10
	v_sub_u32_e32 v1, 0xd7f, v246
	v_lshrrev_b32_e32 v2, 9, v1
	s_add_u32 s8, s34, 0x300000
	v_add_u32_e32 v1, 2, v2
	v_add_u32_e32 v247, 0x200, v246
	s_addc_u32 s9, s35, 0
	v_and_b32_e32 v3, 14, v1
	v_mov_b32_e32 v1, v2
	s_mov_b64 s[10:11], 0
	s_mov_b32 s7, 1
	v_mov_b32_e32 v5, 0
	s_mov_b32 s12, s6
	v_mov_b64_e32 v[6:7], v[246:247]
	s_branch .LBB0_5
